# prompt attention: K/V/F tiles prefetched two tiles ahead in alternating register sets, rotating K-fragment buffers; pass C state prefetch
# speedup vs baseline: 1.0032x; 1.0032x over previous
; #define LAS __attribute__((address_space(3)))
; template <bool SAMPLE>
; __device__ __forceinline__ void attn_unit(const Params& p, LAS unsigned char* lds, int unit, int tid, int lane, int wave, float thr) {
;     ...
;     { const bf16_t* qp = Qw + (qrow0 + qoff + r32) * 1024 + head * 64 + 8 * h2;
; #pragma unroll
;       for (int ks = 0; ks < 4; ++ks) qf[ks] = *(const bf16x8*)(qp + 16 * ks);
;       const short one = h2 == 0 ? (short)0x3f80 : (short)0; qf[4] = (bf16x8){one, one, one, 0, 0, 0, 0, 0}; }
;     const int qpos = t0 + qoff + r32;
;     float mrun = -INFINITY, lrun = 0.f; f32x16 o0 = {}, o1 = {};
;     u32x4 kreg[SAMPLE ? 4 : 1], vreg[SAMPLE ? 4 : 1]; float freg = 0.f;
;     const bool active = !SAMPLE || wave < 4;
;     const int lkey = tid >> 3, lchunk = tid & 7;
;     ...
;     const LAS unsigned char* kbase = Kt + slot * TILEB + r32 * KROW + 16 * h2;
;     const LAS unsigned char* vbase = Vt + slot * TILEB + (4 * h2 + ((lane & 15) >> 2)) * KROW + (16 * ((lane >> 4) & 1) + 4 * (lane & 3)) * 2;
;     const int qmax_w = t0 + qoff + 31;
;     for (int j = jstart; j < jend; ++j) {
;         if (j + 1 < jend) ATT_ISSUE(j + 1);
.LBB0_609:
	s_or_b64 exec, exec, s[10:11]
	v_lshlrev_b32_e32 v100, 2, v11
	v_lshrrev_b32_e32 v3, 2, v9
	v_and_or_b32 v3, v3, 3, v100
	v_mul_lo_u32 v3, v3, s48
	v_cmp_gt_u32_e32 vcc, 32, v9
	v_add_u32_e32 v20, 0, v3
	v_and_b32_e32 v3, 16, v9
	v_lshlrev_b32_e32 v5, 2, v9
	s_lshl_b32 s10, s9, 1
	s_and_b32 s9, s9, 63
	v_cndmask_b32_e32 v2, 0, v230, vcc
	v_and_or_b32 v3, v5, 12, v3
	s_lshl_b32 s34, s9, 2
	s_mov_b32 s9, s35
	s_add_i32 s14, s33, s14
	v_lshlrev_b32_e32 v21, 1, v3
	v_perm_b32 v95, 0, v2, v231
	v_perm_b32 v94, v2, v2, s53
	v_lshlrev_b64 v[2:3], 11, v[6:7]
	v_mov_b64_e32 v[6:7], s[8:9]
	s_add_i32 s7, s15, 4
	s_or_b32 s15, s14, 31
	s_and_b32 s10, s10, 0x780
	v_cmp_lt_u64_e32 vcc, s[34:35], v[6:7]
	v_or3_b32 v2, v2, s10, v12
	s_and_b64 s[10:11], vcc, exec
	s_cselect_b32 s8, s34, s8
	v_lshl_add_u64 v[2:3], s[80:81], 0, v[2:3]
	s_lshl_b32 s34, s8, 17
	v_mov_b32_e32 v16, v4
	v_mov_b32_e32 v17, v4
	v_or_b32_e32 v106, s14, v10
	v_mad_u32_u24 v107, v10, s48, 0
	v_lshlrev_b32_e32 v19, 4, v11
	v_add_u32_e32 v108, 64, v8
	v_lshl_add_u64 v[102:103], v[2:3], 0, s[34:35]
	v_mov_b32_e32 v2, v4
	v_mov_b32_e32 v3, v4
	v_mov_b32_e32 v5, v4
	v_mov_b32_e32 v6, v4
	v_mov_b32_e32 v7, v4
	v_mov_b32_e32 v8, v4
	v_mov_b32_e32 v9, v4
	v_mov_b32_e32 v10, v4
	v_mov_b32_e32 v11, v4
	v_mov_b32_e32 v12, v4
	v_mov_b32_e32 v13, v4
	v_mov_b32_e32 v14, v4
	v_mov_b32_e32 v15, v4
	v_mov_b64_e32 v[36:37], v[16:17]
	v_add_u32_e32 v110, v107, v19
	v_add_u32_e32 v111, v20, v21
	v_add_u32_e32 v112, 0, v18
	v_mov_b64_e32 v[34:35], v[14:15]
	v_mov_b64_e32 v[32:33], v[12:13]
	v_mov_b64_e32 v[30:31], v[10:11]
	v_mov_b64_e32 v[28:29], v[8:9]
	v_mov_b64_e32 v[26:27], v[6:7]
	v_mov_b64_e32 v[24:25], v[4:5]
	v_mov_b64_e32 v[22:23], v[2:3]
	v_mov_b64_e32 v[20:21], v[16:17]
	v_mov_b32_e32 v96, s56
	v_mov_b32_e32 v97, s56
	s_add_i32 s33, s13, 1
	v_mov_b32_e32 v113, 0xff800000
	v_mov_b32_e32 v109, 0
	v_mov_b64_e32 v[18:19], v[14:15]
	v_mov_b64_e32 v[16:17], v[12:13]
	v_mov_b64_e32 v[14:15], v[10:11]
	v_mov_b64_e32 v[12:13], v[8:9]
	v_mov_b64_e32 v[10:11], v[6:7]
	v_mov_b64_e32 v[8:9], v[4:5]
	v_mov_b64_e32 v[6:7], v[2:3]
	s_waitcnt lgkmcnt(0)
	v_add_co_u32_e32 v2, vcc, 0x4200000, v102
	s_nop 1
	v_addc_co_u32_e32 v3, vcc, 0, v103, vcc
	s_bitcmp1_b32 s33, 0
	s_cbranch_scc1 .Lpa_pre_b
	global_load_dwordx4 v[86:89], v[102:103], off
	global_load_dwordx4 v[90:93], v[2:3], off
	v_add_u32_e32 v2, s6, v108
	v_ashrrev_i32_e32 v3, 31, v2
	v_lshl_add_u64 v[2:3], v[2:3], 2, s[4:5]
	global_load_dword v104, v[2:3], off
	s_branch .Lpa_pre_done
.Lpa_pre_b:
	global_load_dwordx4 v[238:241], v[102:103], off
	global_load_dwordx4 v[242:245], v[2:3], off
	v_add_u32_e32 v2, s6, v108
	v_ashrrev_i32_e32 v3, 31, v2
	v_lshl_add_u64 v[2:3], v[2:3], 2, s[4:5]
	global_load_dword v246, v[2:3], off
.Lpa_pre_done:
	s_mov_b64 s[8:9], 0x20000
	v_lshl_add_u64 v[102:103], v[102:103], 0, s[8:9]
	s_barrier
	s_branch .LBB0_612

; #define LAS __attribute__((address_space(3)))
; template <bool SAMPLE>
; __device__ __forceinline__ void attn_unit(const Params& p, LAS unsigned char* lds, int unit, int tid, int lane, int wave, float thr) {
;     ...
;     for (int j = jstart; j < jend; ++j) {
;         if (j + 1 < jend) ATT_ISSUE(j + 1);
;         if (active && 64 * j <= qmax_w) {
;             f32x16 sA = {}, sB = {};
; #pragma unroll
;             for (int ks = 0; ks < 4; ++ks) {
;                 const bf16x8 ka = *(const LAS bf16x8*)(kbase + 32 * ks), kb = *(const LAS bf16x8*)(kbase + 32 * KROW + 32 * ks);
;                 sA = __builtin_amdgcn_mfma_f32_32x32x16_bf16(ka, qf[ks], sA, 0, 0, 0); sB = __builtin_amdgcn_mfma_f32_32x32x16_bf16(kb, qf[ks], sB, 0, 0, 0);
;             }
;             { const bf16x8 ka = *(const LAS bf16x8*)(kbase - 16 * h2 + 128), kb = *(const LAS bf16x8*)(kbase - 16 * h2 + 32 * KROW + 128);
;               sA = __builtin_amdgcn_mfma_f32_32x32x16_bf16(ka, qf[4], sA, 0, 0, 0); sB = __builtin_amdgcn_mfma_f32_32x32x16_bf16(kb, qf[4], sB, 0, 0, 0); }
;             if (64 * j + 63 > t0 + qoff) {
;                 const int kb0 = 64 * j + 4 * h2;
; #pragma unroll
;                 for (int r = 0; r < 16; ++r) { const int kv = kb0 + (r & 3) + 8 * (r >> 2); if (kv > qpos) sA[r] = -INFINITY; if (kv + 32 > qpos) sB[r] = -INFINITY; }
;             }
.LBB0_612:
	s_cmp_lt_u32 s33, s7
	s_cselect_b64 s[8:9], -1, 0
	s_add_i32 s10, s33, 1
	s_cmp_ge_u32 s10, s7
	s_cbranch_scc1 .LBB0_616
	v_add_co_u32_e32 v2, vcc, 0x4200000, v102
	s_nop 1
	v_addc_co_u32_e32 v3, vcc, 0, v103, vcc
	s_bitcmp1_b32 s13, 0
	s_cbranch_scc1 .Lpa_issue_b
	global_load_dwordx4 v[86:89], v[102:103], off
	global_load_dwordx4 v[90:93], v[2:3], off
	v_add_u32_e32 v2, s6, v108
	v_add_u32_e32 v2, 64, v2
	v_ashrrev_i32_e32 v3, 31, v2
	v_lshl_add_u64 v[2:3], v[2:3], 2, s[4:5]
	global_load_dword v104, v[2:3], off
	s_branch .LBB0_616
.Lpa_issue_b:
	global_load_dwordx4 v[238:241], v[102:103], off
	global_load_dwordx4 v[242:245], v[2:3], off
	v_add_u32_e32 v2, s6, v108
	v_add_u32_e32 v2, 64, v2
	v_ashrrev_i32_e32 v3, 31, v2
	v_lshl_add_u64 v[2:3], v[2:3], 2, s[4:5]
	global_load_dword v246, v[2:3], off
.LBB0_616:
	s_cmp_gt_i32 s6, s15
	s_cbranch_scc1 .LBB0_620
	ds_read_b128 v[114:117], v110
	ds_read_b128 v[118:121], v110 offset:4608
	ds_read_b128 v[122:125], v110 offset:32
	ds_read_b128 v[126:129], v110 offset:4640
	s_add_i32 s10, s6, 63
	s_waitcnt lgkmcnt(3)
	v_mfma_f32_32x32x16_bf16 v[54:69], v[114:117], v[70:73], 0
	ds_read_b128 v[114:117], v110 offset:64
	s_waitcnt lgkmcnt(3)
	v_mfma_f32_32x32x16_bf16 v[38:53], v[118:121], v[70:73], 0
	ds_read_b128 v[118:121], v110 offset:4672
	s_waitcnt lgkmcnt(3)
	v_mfma_f32_32x32x16_bf16 v[54:69], v[122:125], v[74:77], v[54:69]
	ds_read_b128 v[122:125], v110 offset:96
	s_waitcnt lgkmcnt(3)
	v_mfma_f32_32x32x16_bf16 v[38:53], v[126:129], v[74:77], v[38:53]
	ds_read_b128 v[126:129], v110 offset:4704
	s_waitcnt lgkmcnt(3)
	v_mfma_f32_32x32x16_bf16 v[54:69], v[114:117], v[78:81], v[54:69]
	ds_read_b128 v[114:117], v107 offset:128
	s_waitcnt lgkmcnt(3)
	v_mfma_f32_32x32x16_bf16 v[38:53], v[118:121], v[78:81], v[38:53]
	ds_read_b128 v[118:121], v107 offset:4736
	s_waitcnt lgkmcnt(3)
	v_mfma_f32_32x32x16_bf16 v[54:69], v[122:125], v[82:85], v[54:69]
	s_waitcnt lgkmcnt(2)
	v_mfma_f32_32x32x16_bf16 v[38:53], v[126:129], v[82:85], v[38:53]
	s_waitcnt lgkmcnt(1)
	v_mfma_f32_32x32x16_bf16 v[54:69], v[114:117], v[94:97], v[54:69]
	s_waitcnt lgkmcnt(0)
	v_mfma_f32_32x32x16_bf16 v[38:53], v[118:121], v[94:97], v[38:53]
	s_cmp_le_i32 s10, s14
	s_cbranch_scc1 .LBB0_619
	v_add_u32_e32 v2, s6, v100
	v_add_u32_e32 v3, 32, v2
	v_cmp_le_i32_e32 vcc, v3, v106
	v_add_u32_e32 v3, 33, v2
	s_nop 6
	v_cndmask_b32_e32 v38, v232, v38, vcc
	v_cmp_lt_i32_e32 vcc, v2, v106
	s_nop 1
	v_cndmask_b32_e32 v55, v232, v55, vcc
	v_cmp_le_i32_e32 vcc, v2, v106
	s_nop 1
	v_cndmask_b32_e32 v54, v232, v54, vcc
	v_cmp_le_i32_e32 vcc, v3, v106
	v_add_u32_e32 v3, 2, v2
	s_nop 0
	v_cndmask_b32_e32 v39, v232, v39, vcc
	v_cmp_le_i32_e32 vcc, v3, v106
	v_add_u32_e32 v3, 34, v2
	s_nop 0
	v_cndmask_b32_e32 v56, v232, v56, vcc
	v_cmp_le_i32_e32 vcc, v3, v106
	v_add_u32_e32 v3, 3, v2
	s_nop 0
	v_cndmask_b32_e32 v40, v232, v40, vcc
	v_cmp_le_i32_e32 vcc, v3, v106
	v_add_u32_e32 v3, 35, v2
	s_nop 0
	v_cndmask_b32_e32 v57, v232, v57, vcc
	v_cmp_le_i32_e32 vcc, v3, v106
	v_add_u32_e32 v3, 8, v2
	s_nop 0
	v_cndmask_b32_e32 v41, v232, v41, vcc
	v_cmp_le_i32_e32 vcc, v3, v106
	v_add_u32_e32 v3, 40, v2
	s_nop 0
	v_cndmask_b32_e32 v58, v232, v58, vcc
	v_cmp_le_i32_e32 vcc, v3, v106
	v_add_u32_e32 v3, 9, v2
	s_nop 0
	v_cndmask_b32_e32 v42, v232, v42, vcc
	v_cmp_le_i32_e32 vcc, v3, v106
	v_add_u32_e32 v3, 41, v2
	s_nop 0
	v_cndmask_b32_e32 v59, v232, v59, vcc
	v_cmp_le_i32_e32 vcc, v3, v106
	v_add_u32_e32 v3, 10, v2
	s_nop 0
	v_cndmask_b32_e32 v43, v232, v43, vcc
	v_cmp_le_i32_e32 vcc, v3, v106
	v_add_u32_e32 v3, 42, v2
	s_nop 0
	v_cndmask_b32_e32 v60, v232, v60, vcc
	v_cmp_le_i32_e32 vcc, v3, v106
	v_add_u32_e32 v3, 11, v2
	s_nop 0
	v_cndmask_b32_e32 v44, v232, v44, vcc
	v_cmp_le_i32_e32 vcc, v3, v106
	v_add_u32_e32 v3, 43, v2
	s_nop 0
	v_cndmask_b32_e32 v61, v232, v61, vcc
	v_cmp_le_i32_e32 vcc, v3, v106
	v_add_u32_e32 v3, 16, v2
	s_nop 0
	v_cndmask_b32_e32 v45, v232, v45, vcc
	v_cmp_le_i32_e32 vcc, v3, v106
	v_add_u32_e32 v3, 48, v2
	s_nop 0
	v_cndmask_b32_e32 v62, v232, v62, vcc
	v_cmp_le_i32_e32 vcc, v3, v106
	v_add_u32_e32 v3, 17, v2
	s_nop 0
	v_cndmask_b32_e32 v46, v232, v46, vcc
	v_cmp_le_i32_e32 vcc, v3, v106
	v_add_u32_e32 v3, 49, v2
	s_nop 0
	v_cndmask_b32_e32 v63, v232, v63, vcc
	v_cmp_le_i32_e32 vcc, v3, v106
	v_add_u32_e32 v3, 18, v2
	s_nop 0
	v_cndmask_b32_e32 v47, v232, v47, vcc
	v_cmp_le_i32_e32 vcc, v3, v106
	v_add_u32_e32 v3, 50, v2
	s_nop 0
	v_cndmask_b32_e32 v64, v232, v64, vcc
	v_cmp_le_i32_e32 vcc, v3, v106
	v_add_u32_e32 v3, 19, v2
	s_nop 0
	v_cndmask_b32_e32 v48, v232, v48, vcc
	v_cmp_le_i32_e32 vcc, v3, v106
	v_add_u32_e32 v3, 51, v2
	s_nop 0
	v_cndmask_b32_e32 v65, v232, v65, vcc
	v_cmp_le_i32_e32 vcc, v3, v106
	v_add_u32_e32 v3, 24, v2
	s_nop 0
	v_cndmask_b32_e32 v49, v232, v49, vcc
	v_cmp_le_i32_e32 vcc, v3, v106
	v_add_u32_e32 v3, 56, v2
	s_nop 0
	v_cndmask_b32_e32 v66, v232, v66, vcc
	v_cmp_le_i32_e32 vcc, v3, v106
	v_add_u32_e32 v3, 25, v2
	s_nop 0
	v_cndmask_b32_e32 v50, v232, v50, vcc
	v_cmp_le_i32_e32 vcc, v3, v106
	v_add_u32_e32 v3, 57, v2
	s_nop 0
	v_cndmask_b32_e32 v67, v232, v67, vcc
	v_cmp_le_i32_e32 vcc, v3, v106
	v_add_u32_e32 v3, 26, v2
	s_nop 0
	v_cndmask_b32_e32 v51, v232, v51, vcc
	v_cmp_le_i32_e32 vcc, v3, v106
	v_add_u32_e32 v3, 58, v2
	s_nop 0
	v_cndmask_b32_e32 v68, v232, v68, vcc
	v_cmp_le_i32_e32 vcc, v3, v106
	v_add_u32_e32 v3, 27, v2
	v_add_u32_e32 v2, 59, v2
	v_cndmask_b32_e32 v52, v232, v52, vcc
	v_cmp_le_i32_e32 vcc, v3, v106
	s_nop 1
	v_cndmask_b32_e32 v69, v232, v69, vcc
	v_cmp_le_i32_e32 vcc, v2, v106
	s_nop 1
	v_cndmask_b32_e32 v53, v232, v53, vcc
; template <bool SAMPLE>
; __device__ __forceinline__ void attn_unit(const Params& p, LAS unsigned char* lds, int unit, int tid, int lane, int wave, float thr) {
;     ...
;             float mx = fmaxf(sA[0], sB[0]);
; #pragma unroll
;             for (int r = 1; r < 16; ++r) mx = fmaxf(mx, fmaxf(sA[r], sB[r]));
;             mx = fmaxf(mx, __shfl_xor(mx, 32));
;             const float mnew = fmaxf(mrun, mx); const float alpha = __builtin_amdgcn_exp2f(mrun - mnew); mrun = mnew;
;             float ls = 0.f;
; #pragma unroll
;             for (int r = 0; r < 16; ++r) { sA[r] = __builtin_amdgcn_exp2f(sA[r] - mnew); sB[r] = __builtin_amdgcn_exp2f(sB[r] - mnew); ls += sA[r] + sB[r]; }
;             lrun = lrun * alpha + ls;
; #pragma unroll
;             for (int r = 0; r < 16; ++r) { o0[r] *= alpha; o1[r] *= alpha; }
;             bf16x8 pf[4];
;             { u32x4 w;
;               w.x = pk2(sA[0], sA[1]); w.y = pk2(sA[2], sA[3]); w.z = pk2(sA[4], sA[5]); w.w = pk2(sA[6], sA[7]); pf[0] = __builtin_bit_cast(bf16x8, w);
;               w.x = pk2(sA[8], sA[9]); w.y = pk2(sA[10], sA[11]); w.z = pk2(sA[12], sA[13]); w.w = pk2(sA[14], sA[15]); pf[1] = __builtin_bit_cast(bf16x8, w);
;               w.x = pk2(sB[0], sB[1]); w.y = pk2(sB[2], sB[3]); w.z = pk2(sB[4], sB[5]); w.w = pk2(sB[6], sB[7]); pf[2] = __builtin_bit_cast(bf16x8, w);
;               w.x = pk2(sB[8], sB[9]); w.y = pk2(sB[10], sB[11]); w.z = pk2(sB[12], sB[13]); w.w = pk2(sB[14], sB[15]); pf[3] = __builtin_bit_cast(bf16x8, w); }
; #pragma unroll
;             for (int ks = 0; ks < 4; ++ks) {
;                 const s16x4 a0 = vtr(vbase + (16 * ks) * KROW), a1 = vtr(vbase + (16 * ks + 8) * KROW);
;                 const s16x4 c0 = vtr(vbase + (16 * ks) * KROW + 64), c1 = vtr(vbase + (16 * ks + 8) * KROW + 64);
;                 const bf16x8 va = (bf16x8){a0[0], a0[1], a0[2], a0[3], a1[0], a1[1], a1[2], a1[3]}, vc = (bf16x8){c0[0], c0[1], c0[2], c0[3], c1[0], c1[1], c1[2], c1[3]};
;                 o0 = __builtin_amdgcn_mfma_f32_32x32x16_bf16(va, pf[ks], o0, 0, 0, 0); o1 = __builtin_amdgcn_mfma_f32_32x32x16_bf16(vc, pf[ks], o1, 0, 0, 0);
;             }
;         }
;         __syncthreads();
;         if (j + 1 < jend) ATT_STASH(j + 1);
;         __syncthreads();
.LBB0_619:
	ds_read_b64_tr_b16 v[114:115], v111 offset:9216
	ds_read_b64_tr_b16 v[116:117], v111 offset:10368
	ds_read_b64_tr_b16 v[118:119], v111 offset:9280
	ds_read_b64_tr_b16 v[120:121], v111 offset:10432
	ds_read_b64_tr_b16 v[122:123], v111 offset:11520
	ds_read_b64_tr_b16 v[124:125], v111 offset:12672
	ds_read_b64_tr_b16 v[126:127], v111 offset:11584
	ds_read_b64_tr_b16 v[128:129], v111 offset:12736
	s_nop 3
	v_max3_f32 v2, v54, v55, v56
	v_max3_f32 v3, v38, v39, v40
	v_max3_f32 v2, v2, v57, v58
	v_max3_f32 v3, v3, v41, v42
	v_max3_f32 v2, v2, v59, v60
	v_max3_f32 v3, v3, v43, v44
	v_max3_f32 v2, v2, v61, v62
	v_max3_f32 v3, v3, v45, v46
	v_max3_f32 v2, v2, v63, v64
	v_max3_f32 v3, v3, v47, v48
	v_max3_f32 v2, v2, v65, v66
	v_max3_f32 v3, v3, v49, v50
	v_max3_f32 v2, v2, v67, v68
	v_max3_f32 v3, v3, v51, v52
	v_max3_f32 v2, v2, v3, v69
	v_max_f32_e32 v2, v2, v53
	v_mov_b32_e32 v3, v2
	s_nop 1
	v_permlane32_swap_b32_e32 v2, v3
	v_max3_f32 v3, v113, v2, v3
	v_sub_f32_e32 v54, v54, v3
	v_sub_f32_e32 v55, v55, v3
	v_exp_f32_e32 v54, v54
	v_exp_f32_e32 v55, v55
	v_sub_f32_e32 v56, v56, v3
	v_sub_f32_e32 v57, v57, v3
	v_exp_f32_e32 v56, v56
	v_exp_f32_e32 v57, v57
	v_sub_f32_e32 v58, v58, v3
	v_sub_f32_e32 v59, v59, v3
	v_exp_f32_e32 v58, v58
	v_exp_f32_e32 v59, v59
	v_sub_f32_e32 v60, v60, v3
	v_sub_f32_e32 v61, v61, v3
	v_exp_f32_e32 v60, v60
	v_exp_f32_e32 v61, v61
	v_sub_f32_e32 v62, v62, v3
	v_sub_f32_e32 v63, v63, v3
	v_exp_f32_e32 v62, v62
	v_exp_f32_e32 v63, v63
	v_sub_f32_e32 v64, v64, v3
	v_sub_f32_e32 v65, v65, v3
	v_exp_f32_e32 v64, v64
	v_exp_f32_e32 v65, v65
	v_sub_f32_e32 v66, v66, v3
	v_sub_f32_e32 v67, v67, v3
	v_exp_f32_e32 v66, v66
	v_exp_f32_e32 v67, v67
	v_sub_f32_e32 v68, v68, v3
	v_sub_f32_e32 v69, v69, v3
	v_exp_f32_e32 v68, v68
	v_exp_f32_e32 v69, v69
	v_sub_f32_e32 v38, v38, v3
	v_sub_f32_e32 v39, v39, v3
	v_exp_f32_e32 v38, v38
	v_exp_f32_e32 v39, v39
	v_sub_f32_e32 v40, v40, v3
	v_sub_f32_e32 v41, v41, v3
	v_exp_f32_e32 v40, v40
	v_exp_f32_e32 v41, v41
	v_sub_f32_e32 v42, v42, v3
	v_sub_f32_e32 v43, v43, v3
	v_exp_f32_e32 v42, v42
	v_exp_f32_e32 v43, v43
	v_sub_f32_e32 v44, v44, v3
	v_sub_f32_e32 v45, v45, v3
	v_exp_f32_e32 v44, v44
	v_exp_f32_e32 v45, v45
	v_sub_f32_e32 v46, v46, v3
	v_sub_f32_e32 v47, v47, v3
	v_exp_f32_e32 v46, v46
	v_exp_f32_e32 v47, v47
	v_sub_f32_e32 v48, v48, v3
	v_sub_f32_e32 v49, v49, v3
	v_exp_f32_e32 v48, v48
	v_exp_f32_e32 v49, v49
	v_sub_f32_e32 v50, v50, v3
	v_sub_f32_e32 v51, v51, v3
	v_exp_f32_e32 v50, v50
	v_exp_f32_e32 v51, v51
	v_sub_f32_e32 v52, v52, v3
	v_sub_f32_e32 v53, v53, v3
	v_exp_f32_e32 v52, v52
	v_exp_f32_e32 v53, v53
	v_add_f32_e32 v5, v54, v55
	v_add_f32_e32 v2, v56, v57
	v_add_f32_e32 v5, v5, v58
	v_add_f32_e32 v2, v2, v59
	v_add_f32_e32 v5, v5, v60
	v_add_f32_e32 v2, v2, v61
	v_add_f32_e32 v5, v5, v62
	v_add_f32_e32 v2, v2, v63
	v_add_f32_e32 v5, v5, v64
	v_add_f32_e32 v2, v2, v65
	v_add_f32_e32 v5, v5, v66
	v_add_f32_e32 v2, v2, v67
	v_add_f32_e32 v5, v5, v68
	v_add_f32_e32 v2, v2, v69
	v_add_f32_e32 v5, v5, v38
	v_add_f32_e32 v2, v2, v39
	v_add_f32_e32 v5, v5, v40
	v_add_f32_e32 v2, v2, v41
	v_add_f32_e32 v5, v5, v42
	v_add_f32_e32 v2, v2, v43
	v_add_f32_e32 v5, v5, v44
	v_add_f32_e32 v2, v2, v45
	v_add_f32_e32 v5, v5, v46
	v_add_f32_e32 v2, v2, v47
	v_add_f32_e32 v5, v5, v48
	v_add_f32_e32 v2, v2, v49
	v_add_f32_e32 v5, v5, v50
	v_add_f32_e32 v2, v2, v51
	v_add_f32_e32 v5, v5, v52
	v_add_f32_e32 v2, v2, v53
	v_add_f32_e32 v5, v5, v2
	v_sub_f32_e32 v2, v113, v3
	v_exp_f32_e32 v2, v2
	v_mov_b32_e32 v113, v3
	s_nop 0
	v_fma_f32 v109, v109, v2, v5
	v_pk_mul_f32 v[36:37], v[36:37], v[2:3] op_sel_hi:[1,0]
	v_pk_mul_f32 v[34:35], v[34:35], v[2:3] op_sel_hi:[1,0]
	v_pk_mul_f32 v[32:33], v[32:33], v[2:3] op_sel_hi:[1,0]
	v_pk_mul_f32 v[30:31], v[30:31], v[2:3] op_sel_hi:[1,0]
	v_pk_mul_f32 v[28:29], v[28:29], v[2:3] op_sel_hi:[1,0]
	v_pk_mul_f32 v[26:27], v[26:27], v[2:3] op_sel_hi:[1,0]
	v_pk_mul_f32 v[24:25], v[24:25], v[2:3] op_sel_hi:[1,0]
	v_pk_mul_f32 v[22:23], v[22:23], v[2:3] op_sel_hi:[1,0]
	v_pk_mul_f32 v[20:21], v[20:21], v[2:3] op_sel_hi:[1,0]
	v_pk_mul_f32 v[18:19], v[18:19], v[2:3] op_sel_hi:[1,0]
	v_pk_mul_f32 v[16:17], v[16:17], v[2:3] op_sel_hi:[1,0]
	v_pk_mul_f32 v[14:15], v[14:15], v[2:3] op_sel_hi:[1,0]
	v_pk_mul_f32 v[12:13], v[12:13], v[2:3] op_sel_hi:[1,0]
	v_pk_mul_f32 v[10:11], v[10:11], v[2:3] op_sel_hi:[1,0]
	v_pk_mul_f32 v[8:9], v[8:9], v[2:3] op_sel_hi:[1,0]
	v_pk_mul_f32 v[6:7], v[6:7], v[2:3] op_sel_hi:[1,0]
	v_cvt_pk_bf16_f32 v54, v54, v55
	v_cvt_pk_bf16_f32 v55, v56, v57
	v_cvt_pk_bf16_f32 v56, v58, v59
	v_cvt_pk_bf16_f32 v57, v60, v61
	v_cvt_pk_bf16_f32 v58, v62, v63
	v_cvt_pk_bf16_f32 v59, v64, v65
	v_cvt_pk_bf16_f32 v60, v66, v67
	v_cvt_pk_bf16_f32 v61, v68, v69
	v_cvt_pk_bf16_f32 v38, v38, v39
	v_cvt_pk_bf16_f32 v39, v40, v41
	v_cvt_pk_bf16_f32 v40, v42, v43
	v_cvt_pk_bf16_f32 v41, v44, v45
	v_cvt_pk_bf16_f32 v42, v46, v47
	v_cvt_pk_bf16_f32 v43, v48, v49
	v_cvt_pk_bf16_f32 v44, v50, v51
	v_cvt_pk_bf16_f32 v45, v52, v53
	ds_read_b64_tr_b16 v[62:63], v111 offset:13824
	ds_read_b64_tr_b16 v[64:65], v111 offset:14976
	ds_read_b64_tr_b16 v[66:67], v111 offset:13888
	ds_read_b64_tr_b16 v[68:69], v111 offset:15040
	ds_read_b64_tr_b16 v[46:47], v111 offset:16128
	ds_read_b64_tr_b16 v[48:49], v111 offset:17280
	ds_read_b64_tr_b16 v[50:51], v111 offset:16192
	ds_read_b64_tr_b16 v[52:53], v111 offset:17344
	s_waitcnt lgkmcnt(8)
	v_mfma_f32_32x32x16_bf16 v[22:37], v[114:117], v[54:57], v[22:37]
	v_mfma_f32_32x32x16_bf16 v[6:21], v[118:121], v[54:57], v[6:21]
	v_mfma_f32_32x32x16_bf16 v[22:37], v[122:125], v[58:61], v[22:37]
	v_mfma_f32_32x32x16_bf16 v[6:21], v[126:129], v[58:61], v[6:21]
	s_waitcnt lgkmcnt(6)
	v_mfma_f32_32x32x16_bf16 v[22:37], v[62:65], v[38:41], v[22:37]
	s_waitcnt lgkmcnt(4)
	v_mfma_f32_32x32x16_bf16 v[6:21], v[66:69], v[38:41], v[6:21]
	s_waitcnt lgkmcnt(2)
	v_mfma_f32_32x32x16_bf16 v[22:37], v[46:49], v[42:45], v[22:37]
	s_waitcnt lgkmcnt(0)
	v_mfma_f32_32x32x16_bf16 v[6:21], v[50:53], v[42:45], v[6:21]
.LBB0_620:
	s_andn2_b64 vcc, exec, s[8:9]
	s_barrier
	s_cbranch_vccnz .LBB0_611
	s_add_i32 s10, s33, 1
	s_cmp_lt_u32 s10, s7
	s_cbranch_scc1 .Lpa_w2
	s_waitcnt vmcnt(0)
	s_branch .Lpa_wdone

.Lpa_wdone:
	s_bitcmp1_b32 s13, 0
	s_cbranch_scc1 .Lpa_st_a
	ds_write_b128 v105, v[238:241]
	ds_write_b128 v105, v[242:245] offset:9216
	v_sub_f32_e32 v2, v246, v101
	s_branch .Lpa_st_common
.Lpa_st_a:
	ds_write_b128 v105, v[86:89]
	ds_write_b128 v105, v[90:93] offset:9216
	v_sub_f32_e32 v2, v104, v101
.Lpa_st_common:
	s_and_saveexec_b64 s[8:9], s[2:3]
	s_cbranch_execz .LBB0_610
	v_mul_f32_e32 v3, 0xbfb8aa3b, v2
	v_and_b32_e32 v5, 0xffff0000, v3
	v_fma_f32 v2, v2, s47, -v5
	v_and_b32_e32 v5, 0xffff0000, v2
	v_sub_f32_e32 v38, v2, v5
	v_or_b32_sdwa v2, v5, v3 dst_sel:DWORD dst_unused:UNUSED_PAD src0_sel:DWORD src1_sel:WORD_1
	v_lshrrev_b32_e32 v3, 16, v38
	v_mov_b32_e32 v5, v4
	ds_write_b128 v112, v[2:5] offset:128
	s_branch .LBB0_610
